# recurrence phase (P5): one static s_setprio 1 for waves 4-7 at phase entry, reset at exit
# speedup vs baseline: 1.0050x; 1.0050x over previous
; #define LAS __attribute__((address_space(3)))
; __device__ __forceinline__ void hgrn_item(LAS unsigned char* lds, int item, const bf16_t* QS, const float* LF, const bf16_t* KK, const bf16_t* VV, bf16_t* YAB) {
;     const int tid = threadIdx.x, lane = tid & 63, wid = tid >> 6, l15 = lane & 15, quad = lane >> 4;
;     const int b = item >> 4, h = (item >> 1) & 7, vh = item & 1;
;     LAS bf16_t* QT = (LAS bf16_t*)(lds + 0);
;     LAS bf16_t* KT = (LAS bf16_t*)(lds + 17408);
;     LAS bf16_t* QH = (LAS bf16_t*)(lds + 34816);
;     LAS bf16_t* KD = (LAS bf16_t*)(lds + 52224);
;     LAS bf16_t* VT = (LAS bf16_t*)(lds + 70656);
;     LAS bf16_t* PP = (LAS bf16_t*)(lds + 79872);
;     LAS bf16_t* ST = (LAS bf16_t*)(lds + 89088);
;     LAS float* DD = (LAS float*)(lds + 106496);
;     LAS float* PS = (LAS float*)(lds + 107008);
;     const int k = tid & 127, part = tid >> 7;
;     const int vv = tid & 63, sg = tid >> 6;
;     const size_t row0 = (size_t)b * SEQ;
;     const int colq = h * 128 + k, colv = h * 128 + vh * 64 + vv;
;     const int tt = wid >> 1, vt0 = (wid & 1) * 2;
;     f32x4 S[4];
; #pragma unroll
;     for (int i = 0; i < 4; ++i) S[i] = (f32x4){0.f, 0.f, 0.f, 0.f};
;     for (int i = tid; i < 64 * 136 / 2; i += NTHREADS) ((LAS unsigned*)ST)[i] = 0u;
;     float lfv[16]; bf16_t qv[16], kv[16], vr[8];
; __global__ void __launch_bounds__(NTHREADS, 2) fwd_kernel(Args args) {
;     ...
;     if (IN(5)) {
;         for (int it = bid; it < 256; it += G) {
;             if (it < 128) hgrn_item(lds, it, QS, LF, KK, VV, YAB);
;             else lru_item(lds, it - 128, XB, GB, conv_w, conv_b, WLA, WLX, lru_ba, lru_bx, lru_lambda, YAB);
;         }
;     }
.LBB0_628:
	s_add_u32 s62, s92, 0x15e00000
	s_addc_u32 s63, s93, 0
	v_writelane_b32 v244, s66, 43
	s_cmp_lt_i32 s94, 6
	s_cselect_b64 s[2:3], -1, 0
	v_writelane_b32 v244, s67, 44
	v_writelane_b32 v244, s2, 45
	s_and_b64 s[0:1], s[2:3], s[0:1]
	s_cmpk_lt_i32 s83, 0x100
	v_writelane_b32 v244, s3, 46
	s_cselect_b64 s[2:3], -1, 0
	s_mov_b64 s[20:21], s[88:89]
	v_writelane_b32 v244, s2, 47
	s_and_b64 s[0:1], s[2:3], s[0:1]
	s_mov_b64 s[22:23], s[90:91]
	s_mov_b64 s[24:25], s[92:93]
	s_mov_b64 s[26:27], s[94:95]
	v_and_b32_e32 v166, 0x70, v179
	v_lshrrev_b32_e32 v167, 7, v177
	v_mov_b32_e32 v27, 0
	s_andn2_b64 vcc, exec, s[0:1]
	s_mov_b32 s15, 1
	v_writelane_b32 v244, s3, 48
	s_cbranch_vccnz .LBB0_712
	v_readfirstlane_b32 s98, v177
	s_nop 3
	s_lshr_b32 s98, s98, 6
	s_cmp_ge_u32 s98, 4
	s_cbranch_scc0 .Lp5_prio_done
	s_setprio 1
.Lp5_prio_done:
	v_writelane_b32 v244, s82, 36
	v_cmp_gt_u32_e64 s[2:3], 64, v177
	v_and_b32_e32 v7, 48, v176
	v_lshrrev_b32_e32 v31, 6, v177
	v_writelane_b32 v244, s2, 49
	v_lshrrev_b32_e32 v0, 4, v176
	v_or_b32_e32 v5, v166, v178
	v_writelane_b32 v244, s3, 50
	v_add_u32_e32 v45, 0, v7
	s_movk_i32 s3, 0x110
	v_lshlrev_b32_e32 v1, 5, v31
	v_mad_u32_u24 v47, v5, s3, v45
	v_lshlrev_b32_e32 v5, 2, v0
	v_and_b32_e32 v37, 32, v1
	v_lshlrev_b32_e32 v6, 3, v0
	v_or_b32_e32 v0, v5, v166
	v_lshlrev_b32_e32 v2, 2, v177
	s_add_i32 s2, 0, 0x19f00
	v_lshlrev_b32_e32 v3, 2, v176
	v_or_b32_e32 v12, v37, v178
	v_mul_u32_u24_e32 v14, 0x41, v0
	v_add_u32_e32 v39, s2, v2
	v_add_u32_e32 v53, s2, v3
	s_movk_i32 s2, 0x41
	v_add_lshl_u32 v15, v14, v12, 2
	s_add_i32 s10, 0, 0x10d00
	s_add_i32 s11, 0, 0x14e00
	v_add_u32_e32 v61, s10, v15
	v_add_u32_e32 v63, 0, v15
	v_add_u32_e32 v65, s11, v15
	v_mad_u32_u24 v15, v0, s2, s2
	v_add_lshl_u32 v16, v15, v12, 2
	v_add_u32_e32 v67, s10, v16
	v_add_u32_e32 v69, s11, v16
	v_mov_b32_e32 v16, 0x82
	v_mad_u32_u24 v16, v0, s2, v16
	v_add_lshl_u32 v17, v16, v12, 2
	v_add_u32_e32 v71, s10, v17
	v_add_u32_e32 v73, s11, v17
	v_mov_b32_e32 v17, 0xc3
	v_or_b32_e32 v13, 16, v12
	v_cmp_eq_u32_e64 s[16:17], 0, v0
	v_mad_u32_u24 v0, v0, s2, v17
	v_mad_u32_u24 v57, v12, s3, v45
	v_add_lshl_u32 v12, v0, v12, 2
	v_add_lshl_u32 v0, v0, v13, 2
	v_add_u32_e32 v75, s10, v12
	v_add_u32_e32 v77, s11, v12
	v_add_lshl_u32 v12, v13, v14, 2
	v_add_u32_e32 v107, s10, v0
	v_add_u32_e32 v108, s11, v0
	v_mul_u32_u24_e32 v0, 0x208, v31
	v_add_u32_e32 v79, s10, v12
	v_add_u32_e32 v85, s11, v12
	v_add_u32_e32 v89, 0, v12
	v_add_lshl_u32 v12, v16, v13, 2
	v_add_lshl_u32 v0, v0, v176, 2
	v_add_u32_e32 v105, s10, v12
	v_add_u32_e32 v106, s11, v12
	v_add_u32_e32 v12, 0x104, v0
	v_add_u32_e32 v111, s10, v12
	v_add_u32_e32 v112, s11, v12
	v_add_u32_e32 v12, 0x208, v0
	v_add_u32_e32 v113, s10, v12
	v_add_u32_e32 v114, s11, v12
	v_add_u32_e32 v12, 0x30c, v0
	v_add_u32_e32 v115, s10, v12
	v_add_u32_e32 v116, s11, v12
	v_add_u32_e32 v12, 0x410, v0
	v_add_u32_e32 v117, s10, v12
	v_add_u32_e32 v118, s11, v12
	v_add_u32_e32 v12, 0x514, v0
	v_add_u32_e32 v109, s10, v0
	v_add_u32_e32 v110, s11, v0
	v_add_u32_e32 v119, s10, v12
	v_add_u32_e32 v120, s11, v12
	v_add_u32_e32 v12, 0x618, v0
	v_add_u32_e32 v0, 0x71c, v0
	v_and_b32_e32 v33, 0x7f, v177
	v_add_u32_e32 v123, s10, v0
	v_add_u32_e32 v124, s11, v0
	v_lshrrev_b32_e32 v0, 5, v177
	v_add_lshl_u32 v14, v15, v13, 2
	v_add_u32_e32 v121, s10, v12
	v_add_u32_e32 v122, s11, v12
	v_lshlrev_b32_e32 v30, 4, v167
	v_and_b32_e32 v12, 2, v0
	s_add_i32 s2, 0, 0x1a200
	v_lshlrev_b32_e32 v0, 2, v33
	v_mad_u32_u24 v59, v13, s3, v45
	v_add_u32_e32 v87, s10, v14
	v_add_u32_e32 v104, s11, v14
	v_add_u32_e32 v125, s2, v2
	v_add_u32_e32 v126, s2, v0
	s_movk_i32 s2, 0x80
	v_mul_u32_u24_e32 v13, 0x90, v33
	v_lshlrev_b32_e32 v14, 5, v167
	v_or_b32_e32 v15, v30, v178
	v_cmp_gt_u32_e64 s[72:73], s2, v177
	v_add3_u32 v127, 0, v13, v14
	v_mul_u32_u24_e32 v13, 0x90, v176
	s_add_i32 s2, 0, 0x11400
	v_lshlrev_b32_e32 v14, 4, v31
	v_mad_u32_u24 v129, v15, s3, v45
	v_mul_u32_u24_e32 v15, 0x90, v15
	s_add_i32 s28, 0, 0x13800
	v_add3_u32 v128, s2, v13, v14
	v_add3_u32 v131, s28, v15, v7
	v_add_u32_e32 v15, s2, v7
	s_add_i32 s2, 0, 0x1a000
	v_add_u32_e32 v134, s2, v0
	v_mul_u32_u24_e32 v0, 0x880, v167
; #define LAS __attribute__((address_space(3)))
; __device__ __forceinline__ void hgrn_item(LAS unsigned char* lds, int item, const bf16_t* QS, const float* LF, const bf16_t* KK, const bf16_t* VV, bf16_t* YAB) {
;     const int tid = threadIdx.x, lane = tid & 63, wid = tid >> 6, l15 = lane & 15, quad = lane >> 4;
;     const int b = item >> 4, h = (item >> 1) & 7, vh = item & 1;
;     LAS bf16_t* QT = (LAS bf16_t*)(lds + 0);
;     LAS bf16_t* KT = (LAS bf16_t*)(lds + 17408);
;     LAS bf16_t* QH = (LAS bf16_t*)(lds + 34816);
;     LAS bf16_t* KD = (LAS bf16_t*)(lds + 52224);
;     LAS bf16_t* VT = (LAS bf16_t*)(lds + 70656);
;     LAS bf16_t* PP = (LAS bf16_t*)(lds + 79872);
;     LAS bf16_t* ST = (LAS bf16_t*)(lds + 89088);
;     LAS float* DD = (LAS float*)(lds + 106496);
;     LAS float* PS = (LAS float*)(lds + 107008);
;     const int k = tid & 127, part = tid >> 7;
;     const int vv = tid & 63, sg = tid >> 6;
;     const size_t row0 = (size_t)b * SEQ;
;     const int colq = h * 128 + k, colv = h * 128 + vh * 64 + vv;
;     const int tt = wid >> 1, vt0 = (wid & 1) * 2;
;     f32x4 S[4];
; #pragma unroll
;     for (int i = 0; i < 4; ++i) S[i] = (f32x4){0.f, 0.f, 0.f, 0.f};
;     for (int i = tid; i < 64 * 136 / 2; i += NTHREADS) ((LAS unsigned*)ST)[i] = 0u;
;     float lfv[16]; bf16_t qv[16], kv[16], vr[8];
; __device__ __forceinline__ void lru_item(LAS unsigned char* lds, int item, const bf16_t* XB, const bf16_t* GB, const float* conv_w, const float* conv_b, const bf16_t* WLA, const bf16_t* WLX,
;                                          const float* ba, const float* bx, const float* lam, bf16_t* YAB) {
;     const int tid = threadIdx.x, lane = tid & 63, wid = tid >> 6, l15 = lane & 15, quad = lane >> 4;
;     const int b = item >> 4, n = (item >> 1) & 7, oh = item & 1;
;     LAS bf16_t* XC = (LAS bf16_t*)(lds + 0);
;     LAS bf16_t* WL = (LAS bf16_t*)(lds + 17408);
;     LAS float* XCF = (LAS float*)(lds + 52224);
;     LAS float* AA = XCF + 64 * 65;
;     LAS float* UU = AA + 64 * 65;
;     LAS float* GA = UU + 64 * 65;
;     LAS float* GH = GA + 512;
;     LAS float* HC = GH + 512;
;     const int ch = tid & 127, part = tid >> 7;
;     const int st = wid >> 1, ct0 = (wid & 1) * 2;
;     const int cl = tid & 63, g = tid >> 6;
;     const size_t row0 = (size_t)b * SEQ;
;     const int colc = n * 128 + ch;
	v_or_b32_e32 v32, 1, v30
	v_or_b32_e32 v0, v0, v33
	v_lshl_add_u32 v43, v33, 1, 0
	v_lshl_add_u32 v135, v0, 1, 0
	v_mul_u32_u24_e32 v0, 0x88, v32
	v_mad_u32_u24 v55, v166, s3, s3
	s_add_i32 s3, 0, 0x15c00
	v_lshl_add_u32 v136, v0, 1, v43
	v_lshlrev_b32_e32 v0, 4, v12
	s_movk_i32 s1, 0x7f
	v_and_b32_e32 v16, 0x3c0, v177
	v_add3_u32 v1, s3, v1, v6
	v_or_b32_e32 v6, v0, v178
	v_cmp_lt_u32_e64 s[94:95], s1, v177
	s_movk_i32 s1, 0x90
	v_or_b32_e32 v13, v5, v30
	v_add_u32_e32 v130, s3, v7
	v_add3_u32 v132, s2, v16, v7
	v_or_b32_e32 v7, v14, v178
	v_cmp_le_u32_e64 s[56:57], v12, v167
	v_cmp_lt_u32_e64 s[48:49], v12, v167
	v_or_b32_e32 v12, 16, v6
	v_mad_u32_u24 v133, v7, s1, v45
	v_mul_u32_u24_e32 v7, 0x90, v13
	v_or_b32_e32 v14, 1, v13
	v_or_b32_e32 v16, 2, v13
	v_or_b32_e32 v17, 3, v13
	v_cmp_gt_u32_e64 s[64:65], v6, v13
	v_cmp_gt_u32_e64 s[92:93], v12, v13
	v_lshlrev_b32_e32 v13, 1, v12
	s_add_i32 s0, 0, 0x18f00
	v_mul_u32_u24_e32 v18, 0x110, v12
	v_mul_u32_u24_e32 v19, 0x90, v12
	v_lshl_add_u32 v22, v6, 1, s28
	v_add3_u32 v138, s28, v7, v13
	v_cmp_gt_u32_e64 s[28:29], v12, v14
	v_cmp_gt_u32_e64 s[30:31], v12, v16
	v_cmp_gt_u32_e64 s[34:35], v12, v17
	v_sub_u32_e32 v12, 0x10ff, v177
	v_add_u32_e32 v49, s0, v2
	s_add_i32 s0, 0, 0x19700
	v_lshrrev_b32_e32 v76, 9, v12
	v_add_u32_e32 v51, s0, v2
	v_add_u32_e32 v12, 2, v76
	v_lshrrev_b32_e32 v144, 4, v177
	v_add_u32_e32 v2, 0, v2
	v_or_b32_e32 v10, 15, v179
	v_and_b32_e32 v142, 30, v12
	v_mul_u32_u24_e32 v12, 0x110, v144
	v_lshlrev_b32_e32 v13, 4, v178
	v_add_u32_e32 v147, 0x16400, v2
	v_add_lshl_u32 v78, v166, v5, 12
	v_and_b32_e32 v2, 64, v177
	v_lshlrev_b32_e32 v80, 1, v178
	v_lshlrev_b32_e32 v28, 3, v31
	v_add_u32_e32 v4, 0, v3
	v_mul_u32_u24_e32 v8, 0x110, v166
	v_mul_u32_u24_e32 v9, 0x104, v166
	v_mul_u32_u24_e32 v11, 0x110, v10
	v_mul_u32_u24_e32 v10, 0x104, v10
	v_mul_u32_u24_e32 v137, 0x110, v6
	v_mul_u32_u24_e32 v20, 0x90, v178
	v_mul_u32_u24_e32 v21, 0x110, v178
	v_cmp_gt_u32_e64 s[42:43], v6, v14
	v_cmp_gt_u32_e64 s[44:45], v6, v16
	v_cmp_gt_u32_e64 s[36:37], v6, v17
	v_mul_u32_u24_e32 v6, 0x90, v6
	v_add3_u32 v12, v12, v13, 0
	v_add_u32_e32 v146, s0, v3
	v_or3_b32 v82, v78, v2, v80
	v_readlane_b32 s0, v245, 1
	v_lshlrev_b32_e32 v2, 8, v177
	v_bfe_u32 v35, v177, 6, 1
	v_cmp_lt_u32_e64 s[4:5], 63, v177
	s_mov_b32 s14, 0
	v_add_u32_e32 v41, -3, v166
	v_cmp_eq_u32_e64 s[12:13], 7, v31
	v_or_b32_e32 v34, 2, v30
	v_or_b32_e32 v36, 3, v30
	v_or_b32_e32 v38, 4, v30
	v_or_b32_e32 v40, 5, v30
	v_or_b32_e32 v42, 6, v30
	v_or_b32_e32 v44, 7, v30
	v_or_b32_e32 v46, 8, v30
	v_or_b32_e32 v48, 9, v30
	v_or_b32_e32 v50, 10, v30
	v_or_b32_e32 v52, 11, v30
	v_or_b32_e32 v54, 12, v30
	v_or_b32_e32 v56, 13, v30
	v_or_b32_e32 v58, 14, v30
	v_or_b32_e32 v60, 15, v30
	v_or_b32_e32 v62, 1, v28
	v_or_b32_e32 v64, 2, v28
	v_or_b32_e32 v66, 3, v28
	v_or_b32_e32 v68, 4, v28
	v_or_b32_e32 v70, 5, v28
	v_or_b32_e32 v72, 6, v28
	v_or_b32_e32 v74, 7, v28
	v_add_u32_e32 v139, 0x90, v138
	v_add_u32_e32 v140, 0x120, v138
	v_add_u32_e32 v141, 0x1b0, v138
	v_mov_b32_e32 v29, v76
	v_lshlrev_b32_e32 v143, 3, v177
	v_add_u32_e32 v145, 0x4400, v12
	v_mov_b32_e32 v83, v27
	s_lshl_b32 s41, s83, 6
	s_lshl_b32 s0, s0, 6
	v_and_b32_e32 v84, 0x3c000, v2
	v_lshlrev_b32_e32 v86, 15, v167
	v_lshlrev_b32_e32 v88, 16, v167
	v_mov_b32_e32 v148, 0x3ecc95a3
	v_add_u32_e32 v149, v43, v8
	v_add_u32_e32 v150, v4, v10
	v_add_u32_e32 v151, v43, v11
	s_mov_b32 s50, 0x41000000
	v_mov_b32_e32 v152, 0x3ab69700
	s_mov_b32 s66, 0x43000000
	s_mov_b32 s67, 0xf800000
	v_mov_b32_e32 v153, 0x260
	s_mov_b32 s40, 0x42b17217
	s_mov_b32 s46, 0xc1880000
	v_lshlrev_b32_e32 v90, 1, v0
	s_mov_b32 s47, 0x5040100
	s_mov_b32 s2, 0xc2a00000
	v_add_u32_e32 v154, v22, v7
	v_add_u32_e32 v155, v130, v18
	v_add_u32_e32 v156, v15, v6
	v_add_u32_e32 v157, v15, v19
	v_add_u32_e32 v158, v15, v20
	v_add_u32_e32 v159, v1, v21
	s_mov_b64 s[52:53], 0x40000
	s_mov_b64 s[54:55], 0x20000
	v_mov_b32_e32 v160, 0x7f800000
	v_mov_b32_e32 v161, 0x7fc00000
	v_mov_b32_e32 v162, 0xff800000
	v_add_u32_e32 v163, v4, v9
	v_mov_b32_e32 v164, 0x7f000000
	v_mov_b32_e32 v165, 0x42a00000
	s_mov_b32 s3, s83
	v_readlane_b32 s1, v245, 2
	v_writelane_b32 v244, s0, 37
	s_branch .LBB0_632

; #define SEAM(k) do { if (lo <= (k) && (k) + 1 < hi) { if ((k) == 0) { asm volatile("s_waitcnt vmcnt(0) lgkmcnt(0)" ::: "memory"); __syncthreads(); grid.sync(); \
;         if (tid == 0) { __builtin_amdgcn_fence(__ATOMIC_ACQUIRE, "agent"); asm volatile("s_waitcnt vmcnt(0)" ::: "memory"); } __syncthreads(); } else { xcd_barrier(xbar); } } } while (0)
; __global__ void __launch_bounds__(NTHREADS, 2) fwd_kernel(Args args) {
;     ...
;     if (IN(5)) {
;         for (int it = bid; it < 256; it += G) {
;             if (it < 128) hgrn_item(lds, it, QS, LF, KK, VV, YAB);
;             else lru_item(lds, it - 128, XB, GB, conv_w, conv_b, WLA, WLX, lru_ba, lru_bx, lru_lambda, YAB);
;         }
;     }
;     SEAM(5);
.LBB0_711:
	s_setprio 0
	v_readlane_b32 s80, v244, 16
	v_readlane_b32 s81, v244, 17
	v_readlane_b32 s82, v244, 36
